# row pass: throw-away loads touch the row after next (software prefetch into L2), counted waits +8
# baseline (speedup 1.0000x reference)
.Lrow_noxn:
	s_and_b64 vcc, exec, s[72:73]
	s_cbranch_vccnz .LBB0_496
	s_waitcnt vmcnt(8)
	s_branch .LBB0_496

.LBB0_504:
	s_or_b64 exec, exec, s[0:1]
	s_add_i32 vcc_lo, s8, s64
	v_readlane_b32 s100, v233, 20
	v_readlane_b32 s101, v233, 21
	s_cmp_lt_i32 vcc_lo, s98
	s_cselect_b32 s100, s100, 0
	s_cselect_b32 s101, s101, 0
	v_lshl_add_u64 v[104:105], s[56:57], 0, v[52:53]
	v_lshl_add_u64 v[104:105], v[104:105], 0, s[100:101]
	v_add_co_u32_e32 v106, vcc, 0x7300000, v104
	s_nop 1
	v_addc_co_u32_e32 v107, vcc, 0, v105, vcc
	v_add_co_u32_e32 v104, vcc, 0x5300000, v104
	s_nop 1
	v_addc_co_u32_e32 v105, vcc, 0, v105, vcc
	global_load_dwordx2 v[108:109], v[104:105], off
	global_load_dwordx2 v[108:109], v[104:105], off offset:512
	global_load_dwordx2 v[108:109], v[104:105], off offset:1024
	global_load_dwordx2 v[108:109], v[104:105], off offset:1536
	global_load_dwordx2 v[110:111], v[106:107], off
	global_load_dwordx2 v[110:111], v[106:107], off offset:512
	global_load_dwordx2 v[110:111], v[106:107], off offset:1024
	global_load_dwordx2 v[110:111], v[106:107], off offset:1536
	s_branch .LBB0_506

.LBB0_506:
	ds_bpermute_b32 v96, v61, v99
	v_lshlrev_b32_e32 v100, 16, v80
	v_and_b32_e32 v101, 0xffff0000, v80
	v_lshlrev_b32_e32 v80, 16, v81
	v_and_b32_e32 v81, 0xffff0000, v81
	s_waitcnt lgkmcnt(0)
	v_add_f32_e32 v96, v99, v96
	ds_bpermute_b32 v99, v90, v96
	v_pk_mul_f32 v[80:81], v[60:61], v[80:81] op_sel_hi:[0,1]
	v_cndmask_b32_e64 v47, v47, v81, s[38:39]
	v_cndmask_b32_e64 v46, v46, v80, s[38:39]
	v_lshlrev_b32_e32 v80, 16, v78
	s_waitcnt lgkmcnt(0)
	v_add_f32_e32 v96, v96, v99
	ds_bpermute_b32 v99, v91, v96
	v_and_b32_e32 v81, 0xffff0000, v78
	v_pk_mul_f32 v[80:81], v[60:61], v[80:81] op_sel_hi:[0,1]
	v_cndmask_b32_e64 v81, v37, v81, s[38:39]
	v_cndmask_b32_e64 v80, v36, v80, s[38:39]
	v_lshlrev_b32_e32 v36, 16, v74
	v_and_b32_e32 v37, 0xffff0000, v74
	s_waitcnt lgkmcnt(0)
	v_add_f32_e32 v74, v96, v99
	ds_bpermute_b32 v96, v92, v74
	v_lshlrev_b32_e32 v78, 16, v79
	v_and_b32_e32 v79, 0xffff0000, v79
	v_pk_mul_f32 v[36:37], v[60:61], v[36:37] op_sel_hi:[0,1]
	v_pk_mul_f32 v[78:79], v[60:61], v[78:79] op_sel_hi:[0,1]
	s_waitcnt lgkmcnt(0)
	v_add_f32_e32 v96, v74, v96
	ds_bpermute_b32 v99, v93, v96
	v_cndmask_b32_e64 v74, v24, v36, s[38:39]
	v_cndmask_b32_e64 v79, v39, v79, s[38:39]
	v_cndmask_b32_e64 v78, v38, v78, s[38:39]
	v_lshlrev_b32_e32 v38, 16, v75
	s_waitcnt lgkmcnt(0)
	v_add_f32_e32 v36, v96, v99
	v_and_b32_e32 v39, 0xffff0000, v75
	v_cndmask_b32_e64 v75, v25, v37, s[38:39]
	ds_bpermute_b32 v37, v94, v36
	v_lshlrev_b32_e32 v24, 16, v72
	v_and_b32_e32 v25, 0xffff0000, v72
	v_pk_mul_f32 v[100:101], v[60:61], v[100:101] op_sel_hi:[0,1]
	v_pk_mul_f32 v[38:39], v[60:61], v[38:39] op_sel_hi:[0,1]
	s_waitcnt lgkmcnt(0)
	v_add_f32_e32 v36, v36, v37
	v_fmamk_f32 v36, v36, 0x3a800000, v153
	v_mul_f32_e32 v37, 0x4f800000, v36
	v_cmp_gt_f32_e32 vcc, s33, v36
	v_pk_mul_f32 v[24:25], v[60:61], v[24:25] op_sel_hi:[0,1]
	v_cndmask_b32_e64 v45, v45, v101, s[38:39]
	v_cndmask_b32_e32 v36, v36, v37, vcc
	v_sqrt_f32_e32 v37, v36
	v_cndmask_b32_e64 v44, v44, v100, s[38:39]
	v_cndmask_b32_e64 v101, v27, v39, s[38:39]
	v_cndmask_b32_e64 v100, v26, v38, s[38:39]
	v_lshlrev_b32_e32 v26, 16, v73
	v_and_b32_e32 v27, 0xffff0000, v73
	v_cndmask_b32_e64 v73, v17, v25, s[38:39]
	v_add_u32_e32 v17, -1, v37
	v_fma_f32 v25, -v17, v37, v36
	v_cmp_ge_f32_e64 s[0:1], 0, v25
	v_add_u32_e32 v25, 1, v37
	v_readlane_b32 s50, v233, 54
	v_cndmask_b32_e64 v17, v37, v17, s[0:1]
	v_fma_f32 v37, -v25, v37, v36
	v_cmp_lt_f32_e64 s[0:1], 0, v37
	v_cndmask_b32_e64 v72, v16, v24, s[38:39]
	v_pk_mul_f32 v[26:27], v[60:61], v[26:27] op_sel_hi:[0,1]
	v_cndmask_b32_e64 v17, v17, v25, s[0:1]
	v_mul_f32_e32 v25, 0x37800000, v17
	v_cndmask_b32_e32 v17, v17, v25, vcc
	v_cmp_class_f32_e32 vcc, v36, v154
	v_cndmask_b32_e64 v102, v18, v26, s[38:39]
	v_cndmask_b32_e64 v103, v19, v27, s[38:39]
	v_cndmask_b32_e32 v17, v17, v36, vcc
	v_div_scale_f32 v25, s[0:1], v17, v17, s50
	v_rcp_f32_e32 v36, v25
	s_nop 0
	v_fma_f32 v16, -v25, v36, 1.0
	v_fmac_f32_e32 v36, v16, v36
	v_div_scale_f32 v16, vcc, s50, v17, s50
	v_mul_f32_e32 v18, v16, v36
	v_fma_f32 v19, -v25, v18, v16
	v_fmac_f32_e32 v18, v19, v36
	v_fma_f32 v16, -v25, v18, v16
	v_div_fmas_f32 v16, v16, v36, v18
	v_div_fixup_f32 v60, v16, v17, s50
	v_lshlrev_b32_e32 v16, 16, v76
	v_and_b32_e32 v17, 0xffff0000, v76
	v_lshlrev_b32_e32 v18, 16, v77
	v_and_b32_e32 v19, 0xffff0000, v77
	v_pk_mul_f32 v[16:17], v[0:1], v[16:17]
	v_pk_mul_f32 v[18:19], v[2:3], v[18:19]
	v_pk_fma_f32 v[36:37], v[16:17], v[60:61], v[44:45] op_sel_hi:[1,0,1]
	v_pk_fma_f32 v[38:39], v[18:19], v[60:61], v[46:47] op_sel_hi:[1,0,1]
	v_lshlrev_b32_e32 v16, 16, v70
	v_and_b32_e32 v17, 0xffff0000, v70
	v_lshlrev_b32_e32 v18, 16, v71
	v_and_b32_e32 v19, 0xffff0000, v71
	v_pk_mul_f32 v[16:17], v[4:5], v[16:17]
	v_pk_mul_f32 v[18:19], v[6:7], v[18:19]
	v_pk_fma_f32 v[24:25], v[16:17], v[60:61], v[80:81] op_sel_hi:[1,0,1]
	v_pk_fma_f32 v[26:27], v[18:19], v[60:61], v[78:79] op_sel_hi:[1,0,1]
	v_lshlrev_b32_e32 v16, 16, v62
	v_and_b32_e32 v17, 0xffff0000, v62
	v_lshlrev_b32_e32 v18, 16, v63
	v_and_b32_e32 v19, 0xffff0000, v63
	v_lshlrev_b32_e32 v44, 16, v58
	v_and_b32_e32 v45, 0xffff0000, v58
	v_lshlrev_b32_e32 v46, 16, v59
	v_and_b32_e32 v47, 0xffff0000, v59
	v_pk_mul_f32 v[16:17], v[8:9], v[16:17]
	v_pk_mul_f32 v[18:19], v[10:11], v[18:19]
	v_pk_mul_f32 v[44:45], v[12:13], v[44:45]
	v_pk_mul_f32 v[46:47], v[14:15], v[46:47]
	v_pk_fma_f32 v[18:19], v[18:19], v[60:61], v[100:101] op_sel_hi:[1,0,1]
	v_pk_fma_f32 v[16:17], v[16:17], v[60:61], v[74:75] op_sel_hi:[1,0,1]
	v_pk_fma_f32 v[46:47], v[46:47], v[60:61], v[102:103] op_sel_hi:[1,0,1]
	s_andn2_b64 vcc, exec, s[72:73]
	v_pk_fma_f32 v[44:45], v[44:45], v[60:61], v[72:73] op_sel_hi:[1,0,1]
	s_cbranch_vccnz .LBB0_508
	v_lshl_add_u64 v[58:59], s[76:77], 0, v[48:49]
	global_store_dwordx4 v[58:59], v[36:39], off nt
	global_store_dwordx4 v[58:59], v[24:27], off offset:1024 nt
	global_store_dwordx4 v[58:59], v[16:19], off offset:2048 nt
	global_store_dwordx4 v[58:59], v[44:47], off offset:3072 nt
	s_waitcnt vmcnt(12)
.LBB0_508:
	s_andn2_b64 vcc, exec, s[74:75]
	s_cbranch_vccnz .Lrow_noxn
	v_pk_mul_f32 v[58:59], v[38:39], v[38:39]
	v_pk_mul_f32 v[62:63], v[36:37], v[36:37]
	s_nop 0
	v_pk_mov_b32 v[70:71], v[62:63], v[58:59] op_sel:[1,0]
	v_mov_b32_e32 v63, v59
	v_pk_add_f32 v[58:59], v[70:71], v[62:63]
	v_pk_mul_f32 v[62:63], v[26:27], v[26:27]
	v_pk_add_f32 v[58:59], v[58:59], v[58:59] op_sel_hi:[0,1]
	v_pk_mul_f32 v[70:71], v[24:25], v[24:25]
	v_mul_f32_e32 v58, v16, v16
	v_pk_mov_b32 v[72:73], v[70:71], v[62:63] op_sel:[1,0]
	v_mov_b32_e32 v71, v63
	v_pk_add_f32 v[62:63], v[72:73], v[70:71]
	v_pk_fma_f32 v[70:71], v[16:17], v[16:17], v[58:59] op_sel_hi:[1,1,0]
	v_mul_f32_e32 v58, v18, v18
	v_pk_add_f32 v[62:63], v[62:63], v[62:63] op_sel_hi:[0,1]
	v_pk_fma_f32 v[72:73], v[18:19], v[18:19], v[58:59] op_sel_hi:[1,1,0]
	v_mul_f32_e32 v70, v44, v44
	v_mul_f32_e32 v72, v45, v45
	v_mul_f32_e32 v58, v46, v46
	v_mul_f32_e32 v62, v47, v47
	v_pk_add_f32 v[70:71], v[70:71], v[72:73]
	v_pk_add_f32 v[58:59], v[58:59], v[62:63]
	s_nop 0
	v_pk_add_f32 v[58:59], v[70:71], v[58:59]
	s_nop 0
	v_add_f32_e32 v58, v58, v59
	ds_bpermute_b32 v59, v61, v58
	s_waitcnt lgkmcnt(0)
	v_add_f32_e32 v58, v58, v59
	ds_bpermute_b32 v59, v90, v58
	s_waitcnt lgkmcnt(0)
	v_add_f32_e32 v58, v58, v59
	ds_bpermute_b32 v59, v91, v58
	s_waitcnt lgkmcnt(0)
	v_add_f32_e32 v58, v58, v59
	ds_bpermute_b32 v59, v92, v58
	s_waitcnt lgkmcnt(0)
	v_add_f32_e32 v58, v58, v59
	ds_bpermute_b32 v59, v93, v58
	s_waitcnt lgkmcnt(0)
	v_add_f32_e32 v58, v58, v59
	ds_bpermute_b32 v59, v94, v58
	s_waitcnt lgkmcnt(0)
	v_add_f32_e32 v58, v58, v59
	v_fmamk_f32 v58, v58, 0x3a800000, v153
	v_mul_f32_e32 v59, 0x4f800000, v58
	v_cmp_gt_f32_e32 vcc, s33, v58
	s_nop 1
	v_cndmask_b32_e32 v60, v58, v59, vcc
	v_sqrt_f32_e32 v62, v60
	v_mov_b32_e32 v58, v36
	v_mov_b32_e32 v59, v38
	v_add_u32_e32 v36, -1, v62
	v_add_u32_e32 v38, 1, v62
	v_fma_f32 v63, -v36, v62, v60
	v_fma_f32 v70, -v38, v62, v60
	v_cmp_ge_f32_e64 s[0:1], 0, v63
	s_nop 1
	v_cndmask_b32_e64 v36, v62, v36, s[0:1]
	v_cmp_lt_f32_e64 s[0:1], 0, v70
	s_nop 1
	v_cndmask_b32_e64 v36, v36, v38, s[0:1]
	v_mul_f32_e32 v38, 0x37800000, v36
	v_cndmask_b32_e32 v36, v36, v38, vcc
	v_cmp_class_f32_e32 vcc, v60, v154
	v_mov_b32_e32 v38, v37
	s_nop 0
	v_cndmask_b32_e32 v36, v36, v60, vcc
	v_div_scale_f32 v60, s[0:1], v36, v36, 1.0
	v_rcp_f32_e32 v62, v60
	v_div_scale_f32 v37, vcc, 1.0, v36, 1.0
	v_fma_f32 v63, -v60, v62, 1.0
	v_fmac_f32_e32 v62, v63, v62
	v_mul_f32_e32 v63, v37, v62
	v_fma_f32 v70, -v60, v63, v37
	v_fmac_f32_e32 v63, v70, v62
	v_fma_f32 v37, -v60, v63, v37
	v_div_fmas_f32 v37, v37, v62, v63
	v_div_fixup_f32 v60, v37, v36, 1.0
	v_pk_mul_f32 v[58:59], v[58:59], v[60:61] op_sel_hi:[1,0]
	v_pk_mul_f32 v[38:39], v[38:39], v[60:61] op_sel_hi:[1,0]
	v_and_b32_sdwa v37, v59, v155 dst_sel:DWORD dst_unused:UNUSED_PAD src0_sel:WORD_1 src1_sel:DWORD
	v_and_b32_sdwa v62, v58, v155 dst_sel:DWORD dst_unused:UNUSED_PAD src0_sel:WORD_1 src1_sel:DWORD
	v_add3_u32 v58, v58, v62, s81
	v_add3_u32 v37, v59, v37, s81
	v_and_b32_sdwa v59, v39, v155 dst_sel:DWORD dst_unused:UNUSED_PAD src0_sel:WORD_1 src1_sel:DWORD
	v_and_b32_sdwa v62, v38, v155 dst_sel:DWORD dst_unused:UNUSED_PAD src0_sel:WORD_1 src1_sel:DWORD
	v_add3_u32 v39, v39, v59, s81
	v_add3_u32 v38, v38, v62, s81
	v_and_b32_e32 v39, 0xffff0000, v39
	v_and_b32_e32 v38, 0xffff0000, v38
	v_or_b32_sdwa v39, v39, v37 dst_sel:DWORD dst_unused:UNUSED_PAD src0_sel:DWORD src1_sel:WORD_1
	v_or_b32_sdwa v38, v38, v58 dst_sel:DWORD dst_unused:UNUSED_PAD src0_sel:DWORD src1_sel:WORD_1
	global_store_dwordx2 v[50:51], v[38:39], off
	v_mov_b32_e32 v38, v24
	v_mov_b32_e32 v39, v26
	v_pk_mul_f32 v[38:39], v[38:39], v[60:61] op_sel_hi:[1,0]
	v_mov_b32_e32 v26, v25
	v_pk_mul_f32 v[24:25], v[26:27], v[60:61] op_sel_hi:[1,0]
	v_and_b32_sdwa v27, v38, v155 dst_sel:DWORD dst_unused:UNUSED_PAD src0_sel:WORD_1 src1_sel:DWORD
	v_add3_u32 v27, v38, v27, s81
	v_and_b32_sdwa v37, v25, v155 dst_sel:DWORD dst_unused:UNUSED_PAD src0_sel:WORD_1 src1_sel:DWORD
	v_and_b32_sdwa v38, v24, v155 dst_sel:DWORD dst_unused:UNUSED_PAD src0_sel:WORD_1 src1_sel:DWORD
	v_and_b32_sdwa v26, v39, v155 dst_sel:DWORD dst_unused:UNUSED_PAD src0_sel:WORD_1 src1_sel:DWORD
	v_add3_u32 v25, v25, v37, s81
	v_add3_u32 v24, v24, v38, s81
	v_add3_u32 v26, v39, v26, s81
	v_and_b32_e32 v25, 0xffff0000, v25
	v_and_b32_e32 v24, 0xffff0000, v24
	v_or_b32_sdwa v25, v25, v26 dst_sel:DWORD dst_unused:UNUSED_PAD src0_sel:DWORD src1_sel:WORD_1
	v_or_b32_sdwa v24, v24, v27 dst_sel:DWORD dst_unused:UNUSED_PAD src0_sel:DWORD src1_sel:WORD_1
	global_store_dwordx2 v[50:51], v[24:25], off offset:512
	v_mov_b32_e32 v24, v16
	v_mov_b32_e32 v25, v18
	v_pk_mul_f32 v[24:25], v[24:25], v[60:61] op_sel_hi:[1,0]
	v_mov_b32_e32 v18, v17
	v_pk_mul_f32 v[16:17], v[18:19], v[60:61] op_sel_hi:[1,0]
	v_and_b32_sdwa v18, v25, v155 dst_sel:DWORD dst_unused:UNUSED_PAD src0_sel:WORD_1 src1_sel:DWORD
	v_and_b32_sdwa v19, v24, v155 dst_sel:DWORD dst_unused:UNUSED_PAD src0_sel:WORD_1 src1_sel:DWORD
	v_add3_u32 v19, v24, v19, s81
	v_add3_u32 v18, v25, v18, s81
	v_and_b32_sdwa v24, v17, v155 dst_sel:DWORD dst_unused:UNUSED_PAD src0_sel:WORD_1 src1_sel:DWORD
	v_and_b32_sdwa v25, v16, v155 dst_sel:DWORD dst_unused:UNUSED_PAD src0_sel:WORD_1 src1_sel:DWORD
	v_add3_u32 v17, v17, v24, s81
	v_add3_u32 v16, v16, v25, s81
	v_and_b32_e32 v17, 0xffff0000, v17
	v_and_b32_e32 v16, 0xffff0000, v16
	v_or_b32_sdwa v17, v17, v18 dst_sel:DWORD dst_unused:UNUSED_PAD src0_sel:DWORD src1_sel:WORD_1
	v_or_b32_sdwa v16, v16, v19 dst_sel:DWORD dst_unused:UNUSED_PAD src0_sel:DWORD src1_sel:WORD_1
	global_store_dwordx2 v[50:51], v[16:17], off offset:1024
	v_mov_b32_e32 v16, v44
	v_mov_b32_e32 v17, v46
	v_pk_mul_f32 v[16:17], v[16:17], v[60:61] op_sel_hi:[1,0]
	v_mov_b32_e32 v46, v45
	v_pk_mul_f32 v[18:19], v[46:47], v[60:61] op_sel_hi:[1,0]
	v_and_b32_sdwa v24, v17, v155 dst_sel:DWORD dst_unused:UNUSED_PAD src0_sel:WORD_1 src1_sel:DWORD
	v_and_b32_sdwa v25, v16, v155 dst_sel:DWORD dst_unused:UNUSED_PAD src0_sel:WORD_1 src1_sel:DWORD
	v_add3_u32 v16, v16, v25, s81
	v_add3_u32 v17, v17, v24, s81
	v_and_b32_sdwa v24, v19, v155 dst_sel:DWORD dst_unused:UNUSED_PAD src0_sel:WORD_1 src1_sel:DWORD
	v_and_b32_sdwa v25, v18, v155 dst_sel:DWORD dst_unused:UNUSED_PAD src0_sel:WORD_1 src1_sel:DWORD
	v_add3_u32 v19, v19, v24, s81
	v_add3_u32 v18, v18, v25, s81
	v_and_b32_e32 v19, 0xffff0000, v19
	v_and_b32_e32 v18, 0xffff0000, v18
	v_or_b32_sdwa v17, v19, v17 dst_sel:DWORD dst_unused:UNUSED_PAD src0_sel:DWORD src1_sel:WORD_1
	v_or_b32_sdwa v16, v18, v16 dst_sel:DWORD dst_unused:UNUSED_PAD src0_sel:DWORD src1_sel:WORD_1
	global_store_dwordx2 v[50:51], v[16:17], off offset:1536
	s_waitcnt vmcnt(12)
	s_and_saveexec_b64 s[0:1], s[42:43]
	s_cbranch_execz .LBB0_495
	v_readlane_b32 s52, v233, 5
	v_readlane_b32 s56, v233, 9
	v_readlane_b32 s57, v233, 10
	s_add_u32 s50, s56, s46
	s_addc_u32 s51, s57, s48
	v_readlane_b32 s53, v233, 6
	v_readlane_b32 s54, v233, 7
	v_readlane_b32 s55, v233, 8
	v_readlane_b32 s58, v233, 11
	v_readlane_b32 s59, v233, 12
	global_store_dword v97, v36, s[50:51]
	s_branch .LBB0_495
